# mixer work queue: first unit per workgroup assigned statically (workgroup i takes attention unit i, later pops offset by 256) and the redundant latch barrier before the loop-top barrier elided
# speedup vs baseline: 1.0075x; 1.0018x over previous
; #define LAS __attribute__((address_space(3)))
; __device__ __forceinline__ int l_tid() { int t = threadIdx.x; asm volatile("" : "+v"(t)); return t; }
; #define WSB(T, off) ((T*)(kargs()->ws + (off)))
; template <int L> __device__ __forceinline__ void layer_body(unsigned char* lds, XcdBarrier& bar) {
;     ...
;             constexpr int NS5 = 16 * (LASTL ? 16 : 18);
;             constexpr int NC = LASTL ? 0 : 32;
;             constexpr int Q_ATT = 0, Q_ATTC = 256, Q_S5 = Q_ATTC + NC, Q_RET = Q_S5 + NS5, Q_RETC = Q_RET + 256, Q_END = Q_RETC + NC;
;             volatile LAS int* qslot = (volatile LAS int*)((LAS unsigned char*)lds + LDS_BYTES - 32);
;             unsigned* s5c_ = kvc_ + 320; bool s5sig_ = false;
;             for (;;) {
;                 __syncthreads();
;                 if (l_tid() == 0) qslot[0] = (int)atomicAdd(WSB(unsigned, WS_BAR) + XCD_BAR_WORDS + 64 * l, 1u);
;                 __syncthreads();
;                 const int q = __builtin_amdgcn_readfirstlane(qslot[0]);
.LBB0_728:
	s_add_u32 s54, s46, 0xc3d00
	s_addc_u32 s55, s47, 0
	s_lshl_b32 s56, s33, 4
	s_mov_b32 s57, 0
	s_lshl_b64 s[4:5], s[56:57], 2
	s_add_u32 s4, s46, s4
	s_addc_u32 s5, s47, s5
	s_add_u32 s58, s4, 0xc3d80
	v_writelane_b32 v254, s48, 4
	s_addc_u32 s59, s5, 0
	s_add_i32 s61, 0, 0x23fe0
	v_writelane_b32 v254, s49, 5
	s_mov_b64 s[70:71], 0
	v_mov_b32_e32 v183, 0xc3000
	v_mov_b32_e32 v206, s61
	s_add_i32 s63, 0, 0x23ff0
	s_waitcnt vmcnt(0)
	v_mov_b32_e32 v130, 0
	s_movk_i32 s65, 0xff
	s_movk_i32 s67, 0xffe0
	s_mov_b32 s48, 0x40000
	s_mov_b32 s49, 0x80000
	s_movk_i32 s93, 0xc0
	s_mov_b32 s95, 0x7f800000
	s_mov_b32 s96, 0x33800000
	v_mov_b32_e32 v207, 0x358637bd
	s_brev_b32 s91, -2
	s_movk_i32 s92, 0x100
	s_movk_i32 s60, 0x208
	s_add_i32 s88, 0, 0x1a100
	s_movk_i32 s62, 0x810
	s_movk_i32 s64, 0x7fff
	s_add_i32 s4, 0, 0x21100
	s_add_i32 s90, 0, 0x1c500
	s_mov_b32 s68, 0x3f200000
	s_mov_b32 s97, 0x3fb8aa3b
	s_mov_b32 s89, 0xc2ce8ed0
	s_mov_b32 s69, 0x42b17218
	v_mov_b32_e32 v208, 0x3ca908c9
	s_mov_b64 s[72:73], 0x9400000
	s_mov_b32 s44, 0x2aaaaaab
	s_mov_b64 s[74:75], 0x4c00740
	s_mov_b32 s45, 0x4c00000
	v_mov_b32_e32 v182, 0x3ecc95a3
	v_mov_b32_e32 v209, 0x7f800000
	v_mov_b32_e32 v210, 0x7fc00000
	v_mov_b32_e32 v211, 0xff800000
	v_mbcnt_hi_u32_b32 v1, -1, v1
	v_bfrev_b32_e32 v212, 1
	v_mov_b32_e32 v213, 0x900
	v_writelane_b32 v254, s4, 6
	s_mov_b32 s99, 1
	s_branch .LBB0_732
.LBB0_729:
.LBB0_730:
	s_mov_b64 s[6:7], 0

; __device__ __forceinline__ int l_tid() { int t = threadIdx.x; asm volatile("" : "+v"(t)); return t; }
; #define WSB(T, off) ((T*)(kargs()->ws + (off)))
; template <int L> __device__ __forceinline__ void layer_body(unsigned char* lds, XcdBarrier& bar) {
;     ...
;             for (;;) {
;                 __syncthreads();
;                 if (l_tid() == 0) qslot[0] = (int)atomicAdd(WSB(unsigned, WS_BAR) + XCD_BAR_WORDS + 64 * l, 1u);
;                 __syncthreads();
;                 const int q = __builtin_amdgcn_readfirstlane(qslot[0]);
.LBB0_732:
	v_mov_b32_e32 v2, v0
	s_barrier
	s_nop 0
	v_cmp_eq_u32_e32 vcc, 0, v2
	s_and_saveexec_b64 s[4:5], vcc
	s_cbranch_execz .LBB0_736
	s_mov_b64 s[6:7], exec
	v_mbcnt_lo_u32_b32 v2, s6, 0
	v_mbcnt_hi_u32_b32 v2, s7, v2
	s_mov_b64 s[10:11], s[0:1]
	v_cmp_eq_u32_e32 vcc, 0, v2
	s_and_saveexec_b64 s[8:9], vcc
	s_cbranch_execz .LBB0_735
	s_cmp_lg_u32 s99, 0
	s_cbranch_scc1 .Lsf_first_a
	s_load_dwordx2 s[10:11], s[10:11], 0xf8
	s_bcnt1_i32_b64 s6, s[6:7]
	v_mov_b32_e32 v3, s6
	s_waitcnt lgkmcnt(0)
	global_atomic_add v3, v183, v3, s[10:11] offset:1536 sc0
	s_waitcnt vmcnt(0)
	v_add_u32_e32 v3, 0x100, v3
	s_branch .LBB0_735
.Lsf_first_a:
	v_mov_b32_e32 v3, s2
	s_mov_b32 s99, 0

; #define LAS __attribute__((address_space(3)))
; __device__ __forceinline__ int l_tid() { int t = threadIdx.x; asm volatile("" : "+v"(t)); return t; }
; #define WSB(T, off) ((T*)(kargs()->ws + (off)))
; template <int L> __device__ __forceinline__ void layer_body(unsigned char* lds, XcdBarrier& bar) {
;     ...
;             constexpr int NS5 = 16 * (LASTL ? 16 : 18);
;             constexpr int NC = LASTL ? 0 : 32;
;             constexpr int Q_ATT = 0, Q_ATTC = 256, Q_S5 = Q_ATTC + NC, Q_RET = Q_S5 + NS5, Q_RETC = Q_RET + 256, Q_END = Q_RETC + NC;
;             volatile LAS int* qslot = (volatile LAS int*)((LAS unsigned char*)lds + LDS_BYTES - 32);
;             unsigned* s5c_ = kvc_ + 320; bool s5sig_ = false;
;             for (;;) {
;                 __syncthreads();
;                 if (l_tid() == 0) qslot[0] = (int)atomicAdd(WSB(unsigned, WS_BAR) + XCD_BAR_WORDS + 64 * l, 1u);
;                 __syncthreads();
;                 const int q = __builtin_amdgcn_readfirstlane(qslot[0]);
.LBB0_2554:
	s_add_u32 s52, s48, 0xc4d00
	s_addc_u32 s53, s49, 0
	s_lshl_b32 s54, s33, 4
	s_mov_b32 s55, 0
	s_lshl_b64 s[4:5], s[54:55], 2
	s_add_u32 s4, s48, s4
	s_addc_u32 s5, s49, s5
	s_add_u32 s56, s4, 0xc4d80
	s_addc_u32 s57, s5, 0
	s_add_i32 s44, 0, 0x23fe0
	s_mov_b64 s[60:61], 0
	v_mov_b32_e32 v183, 0xc3000
	v_mov_b32_e32 v206, s44
	s_add_i32 s45, 0, 0x23ff0
	s_waitcnt vmcnt(0)
	v_mov_b32_e32 v130, 0
	s_movk_i32 s59, 0xffe0
	s_mov_b32 s72, 0x3f2aaaab
	s_mov_b32 s58, 0x3f317218
	s_brev_b32 s73, -2
	s_mov_b32 s74, 0x7f800000
	s_mov_b32 s75, 0x33800000
	s_add_i32 s76, 0, 0x11000
	s_movk_i32 s77, 0xc0
	v_mov_b32_e32 v207, 0x358637bd
	s_movk_i32 s78, 0x100
	s_movk_i32 s79, 0x208
	s_movk_i32 s80, 0x810
	s_movk_i32 s81, 0x7fff
	s_mov_b32 s82, 0x3f200000
	s_mov_b32 s83, 0x3fb8aa3b
	s_mov_b32 s84, 0xc2ce8ed0
	s_mov_b32 s85, 0x42b17218
	v_mov_b32_e32 v208, 0x3ca908c9
	s_mov_b32 s86, 0x2aaaaaab
	s_mov_b32 s87, 0x4c00000
	v_mov_b32_e32 v182, 0x3ecc95a3
	v_mov_b32_e32 v209, 0x7f800000
	v_mov_b32_e32 v210, 0x7fc00000
	v_mov_b32_e32 v211, 0xff800000
	v_mov_b32_e32 v212, 0x900
	v_bfrev_b32_e32 v213, 1
	s_mov_b32 s99, 1
	s_branch .LBB0_2558

; __device__ __forceinline__ int l_tid() { int t = threadIdx.x; asm volatile("" : "+v"(t)); return t; }
; #define WSB(T, off) ((T*)(kargs()->ws + (off)))
; template <int L> __device__ __forceinline__ void layer_body(unsigned char* lds, XcdBarrier& bar) {
;     ...
;             for (;;) {
;                 __syncthreads();
;                 if (l_tid() == 0) qslot[0] = (int)atomicAdd(WSB(unsigned, WS_BAR) + XCD_BAR_WORDS + 64 * l, 1u);
;                 __syncthreads();
;                 const int q = __builtin_amdgcn_readfirstlane(qslot[0]);
.LBB0_2558:
	v_mov_b32_e32 v2, v0
	s_barrier
	s_nop 0
	v_cmp_eq_u32_e32 vcc, 0, v2
	s_and_saveexec_b64 s[4:5], vcc
	s_cbranch_execz .LBB0_2562
	s_mov_b64 s[6:7], exec
	v_mbcnt_lo_u32_b32 v2, s6, 0
	v_mbcnt_hi_u32_b32 v2, s7, v2
	s_mov_b64 s[10:11], s[0:1]
	v_cmp_eq_u32_e32 vcc, 0, v2
	s_and_saveexec_b64 s[8:9], vcc
	s_cbranch_execz .LBB0_2561
	s_cmp_lg_u32 s99, 0
	s_cbranch_scc1 .Lsf_first_b
	s_load_dwordx2 s[10:11], s[10:11], 0xf8
	s_bcnt1_i32_b64 s6, s[6:7]
	v_mov_b32_e32 v3, s6
	s_waitcnt lgkmcnt(0)
	global_atomic_add v3, v183, v3, s[10:11] offset:1792 sc0
	s_waitcnt vmcnt(0)
	v_add_u32_e32 v3, 0x100, v3
	s_branch .LBB0_2561
